# strategy 7.12 loop-edge: v31 + differential-attention unmasked loops: rescale test chain shortened (v_cmp -> s_cbranch_vccz straight to the exp block; 5 fewer scalar ops and one fewer taken branch per
# baseline (speedup 1.0000x reference)
.LBB0_690:
	v_cvt_f32_i32_e32 v4, v0
	s_cmp_eq_u32 s60, s52
	s_cselect_b64 s[44:45], -1, 0
	v_cndmask_b32_e64 v10, v169, 0, s[44:45]
	v_add_u32_e32 v14, s4, v166
	v_fma_f32 v4, -v154, v4, -v10
	ds_read_b128 v[10:13], v14
	s_mov_b32 s20, 2.0
	s_mov_b32 s22, 0x41200000
	s_mov_b32 s24, 0x41800000
	s_mov_b32 s28, 0x41900000
	s_mov_b32 s21, 0x40400000
	s_mov_b32 s23, 0x41300000
	s_mov_b32 s25, 0x41880000
	s_mov_b32 s29, 0x41980000
	v_fma_f32 v80, 0, v154, v4
	v_add_f32_e32 v81, v154, v4
	v_pk_fma_f32 v[82:83], v[154:155], s[20:21], v[4:5] op_sel_hi:[1,1,0]
	v_pk_fma_f32 v[84:85], v[154:155], s[38:39], v[4:5] op_sel_hi:[1,1,0]
	v_pk_fma_f32 v[86:87], v[154:155], s[22:23], v[4:5] op_sel_hi:[1,1,0]
	v_pk_fma_f32 v[88:89], v[154:155], s[24:25], v[4:5] op_sel_hi:[1,1,0]
	v_pk_fma_f32 v[90:91], v[154:155], s[28:29], v[4:5] op_sel_hi:[1,1,0]
	v_pk_fma_f32 v[92:93], v[154:155], s[26:27], v[4:5] op_sel_hi:[1,1,0]
	v_pk_fma_f32 v[94:95], v[154:155], s[36:37], v[4:5] op_sel_hi:[1,1,0]
	v_add_f32_e32 v4, v153, v4
	v_fma_f32 v96, 0, v154, v4
	s_waitcnt vmcnt(6) lgkmcnt(0)
	v_mfma_f32_32x32x16_bf16 v[80:95], v[10:13], v[112:115], v[80:95]
	ds_read_b128 v[10:13], v14 offset:32
	v_add_f32_e32 v97, v154, v4
	v_fma_f32 v98, v154, s20, v4
	v_fma_f32 v99, v155, s21, v4
	v_fma_f32 v100, v154, s38, v4
	v_fma_f32 v101, v155, s39, v4
	v_pk_fma_f32 v[102:103], v[154:155], s[22:23], v[4:5] op_sel_hi:[1,1,0]
	v_pk_fma_f32 v[104:105], v[154:155], s[24:25], v[4:5] op_sel_hi:[1,1,0]
	v_pk_fma_f32 v[106:107], v[154:155], s[28:29], v[4:5] op_sel_hi:[1,1,0]
	s_waitcnt vmcnt(5) lgkmcnt(0)
	v_mfma_f32_32x32x16_bf16 v[80:95], v[10:13], v[116:119], v[80:95]
	ds_read_b128 v[10:13], v14 offset:64
	v_fma_f32 v108, v154, s26, v4
	v_fma_f32 v109, v155, s27, v4
	v_fma_f32 v110, v154, s36, v4
	v_fma_f32 v111, v155, s37, v4
	s_cmp_lg_u32 s60, s52
	s_waitcnt vmcnt(4) lgkmcnt(0)
	v_mfma_f32_32x32x16_bf16 v[80:95], v[10:13], v[120:123], v[80:95]
	ds_read_b128 v[10:13], v14 offset:96
	ds_read_b128 v[170:173], v14 offset:4608
	s_waitcnt vmcnt(3) lgkmcnt(1)
	v_mfma_f32_32x32x16_bf16 v[80:95], v[10:13], v[124:127], v[80:95]
	ds_read_b128 v[10:13], v14 offset:4640
	s_waitcnt lgkmcnt(1)
	v_mfma_f32_32x32x16_bf16 v[96:111], v[170:173], v[112:115], v[96:111]
	s_nop 8
	v_max_f32_e32 v4, v81, v81
	s_waitcnt lgkmcnt(0)
	v_mfma_f32_32x32x16_bf16 v[96:111], v[10:13], v[116:119], v[96:111]
	ds_read_b128 v[10:13], v14 offset:4672
	s_waitcnt lgkmcnt(0)
	v_mfma_f32_32x32x16_bf16 v[96:111], v[10:13], v[120:123], v[96:111]
	ds_read_b128 v[10:13], v14 offset:4704
	s_waitcnt lgkmcnt(0)
	v_mfma_f32_32x32x16_bf16 v[96:111], v[10:13], v[124:127], v[96:111]
	s_nop 11
	v_max3_f32 v10, v97, v82, v98
	v_max3_f32 v4, v4, v83, v99
	v_max3_f32 v10, v10, v80, v96
	v_max3_f32 v4, v4, v84, v100
	v_max3_f32 v10, v10, v85, v101
	v_max3_f32 v4, v4, v86, v102
	v_max3_f32 v10, v10, v87, v103
	v_max3_f32 v4, v4, v88, v104
	v_max3_f32 v10, v10, v89, v105
	v_max3_f32 v4, v4, v90, v106
	v_max3_f32 v10, v10, v91, v107
	v_max3_f32 v4, v4, v92, v108
	v_max3_f32 v10, v10, v93, v109
	v_max3_f32 v4, v4, v94, v110
	v_max3_f32 v10, v10, v95, v111
	v_max_f32_e32 v4, v4, v10
	v_mov_b32_e32 v10, v4
	s_waitcnt lgkmcnt(0)
	s_nop 1
	v_permlane32_swap_b32_e32 v10, v4
	v_max_f32_e32 v4, v4, v10
	v_cmp_lt_f32_e32 vcc, s38, v4
	s_cbranch_scc0 .LBB0_695
	s_cbranch_vccz .LBB0_699
	s_branch .LBB0_696

.LBB0_693:
	v_add_u32_e32 v4, 64, v0
	v_cvt_f32_i32_e32 v4, v4
	s_cmp_eq_u32 s5, s52
	s_cselect_b64 s[44:45], -1, 0
	v_cndmask_b32_e64 v7, v169, 0, s[44:45]
	v_fma_f32 v4, -v154, v4, -v7
	v_add_u32_e32 v7, s62, v166
	ds_read_b128 v[8:11], v7
	s_mov_b32 s20, 2.0
	s_mov_b32 s22, 0x41200000
	s_mov_b32 s24, 0x41800000
	s_mov_b32 s28, 0x41900000
	s_mov_b32 s21, 0x40400000
	s_mov_b32 s23, 0x41300000
	s_mov_b32 s25, 0x41880000
	s_mov_b32 s29, 0x41980000
	v_fma_f32 v80, 0, v154, v4
	v_add_f32_e32 v81, v154, v4
	v_pk_fma_f32 v[82:83], v[154:155], s[20:21], v[4:5] op_sel_hi:[1,1,0]
	v_pk_fma_f32 v[84:85], v[154:155], s[38:39], v[4:5] op_sel_hi:[1,1,0]
	v_pk_fma_f32 v[86:87], v[154:155], s[22:23], v[4:5] op_sel_hi:[1,1,0]
	v_pk_fma_f32 v[88:89], v[154:155], s[24:25], v[4:5] op_sel_hi:[1,1,0]
	v_pk_fma_f32 v[90:91], v[154:155], s[28:29], v[4:5] op_sel_hi:[1,1,0]
	v_pk_fma_f32 v[92:93], v[154:155], s[26:27], v[4:5] op_sel_hi:[1,1,0]
	v_pk_fma_f32 v[94:95], v[154:155], s[36:37], v[4:5] op_sel_hi:[1,1,0]
	v_add_f32_e32 v4, v153, v4
	v_fma_f32 v96, 0, v154, v4
	s_waitcnt vmcnt(6) lgkmcnt(0)
	v_mfma_f32_32x32x16_bf16 v[80:95], v[8:11], v[112:115], v[80:95]
	ds_read_b128 v[8:11], v7 offset:32
	v_add_f32_e32 v97, v154, v4
	v_fma_f32 v98, v154, s20, v4
	v_fma_f32 v99, v155, s21, v4
	v_fma_f32 v100, v154, s38, v4
	v_fma_f32 v101, v155, s39, v4
	v_pk_fma_f32 v[102:103], v[154:155], s[22:23], v[4:5] op_sel_hi:[1,1,0]
	v_pk_fma_f32 v[104:105], v[154:155], s[24:25], v[4:5] op_sel_hi:[1,1,0]
	v_pk_fma_f32 v[106:107], v[154:155], s[28:29], v[4:5] op_sel_hi:[1,1,0]
	s_waitcnt vmcnt(5) lgkmcnt(0)
	v_mfma_f32_32x32x16_bf16 v[80:95], v[8:11], v[116:119], v[80:95]
	ds_read_b128 v[8:11], v7 offset:64
	v_fma_f32 v108, v154, s26, v4
	v_fma_f32 v109, v155, s27, v4
	v_fma_f32 v110, v154, s36, v4
	v_fma_f32 v111, v155, s37, v4
	s_cmp_lg_u32 s5, s52
	s_waitcnt vmcnt(4) lgkmcnt(0)
	v_mfma_f32_32x32x16_bf16 v[80:95], v[8:11], v[120:123], v[80:95]
	ds_read_b128 v[8:11], v7 offset:96
	ds_read_b128 v[12:15], v7 offset:4608
	s_waitcnt vmcnt(3) lgkmcnt(1)
	v_mfma_f32_32x32x16_bf16 v[80:95], v[8:11], v[124:127], v[80:95]
	ds_read_b128 v[8:11], v7 offset:4640
	s_waitcnt lgkmcnt(1)
	v_mfma_f32_32x32x16_bf16 v[96:111], v[12:15], v[112:115], v[96:111]
	s_nop 8
	v_max_f32_e32 v4, v81, v81
	s_waitcnt lgkmcnt(0)
	v_mfma_f32_32x32x16_bf16 v[96:111], v[8:11], v[116:119], v[96:111]
	ds_read_b128 v[8:11], v7 offset:4672
	s_waitcnt lgkmcnt(0)
	v_mfma_f32_32x32x16_bf16 v[96:111], v[8:11], v[120:123], v[96:111]
	ds_read_b128 v[8:11], v7 offset:4704
	s_waitcnt lgkmcnt(0)
	v_mfma_f32_32x32x16_bf16 v[96:111], v[8:11], v[124:127], v[96:111]
	s_nop 11
	v_max3_f32 v7, v97, v82, v98
	v_max3_f32 v4, v4, v83, v99
	v_max3_f32 v7, v7, v80, v96
	v_max3_f32 v4, v4, v84, v100
	v_max3_f32 v7, v7, v85, v101
	v_max3_f32 v4, v4, v86, v102
	v_max3_f32 v7, v7, v87, v103
	v_max3_f32 v4, v4, v88, v104
	v_max3_f32 v7, v7, v89, v105
	v_max3_f32 v4, v4, v90, v106
	v_max3_f32 v7, v7, v91, v107
	v_max3_f32 v4, v4, v92, v108
	v_max3_f32 v7, v7, v93, v109
	v_max3_f32 v4, v4, v94, v110
	v_max3_f32 v7, v7, v95, v111
	v_max_f32_e32 v4, v4, v7
	v_mov_b32_e32 v7, v4
	s_waitcnt lgkmcnt(0)
	s_nop 1
	v_permlane32_swap_b32_e32 v7, v4
	v_max_f32_e32 v4, v4, v7
	v_cmp_lt_f32_e32 vcc, s38, v4
	s_cbranch_scc0 .LBB0_700
	s_cbranch_vccz .LBB0_704
	s_branch .LBB0_701

.LBB0_743:
	v_cvt_f32_i32_e32 v4, v0
	s_cmp_eq_u32 s22, s7
	s_cselect_b64 s[44:45], -1, 0
	v_cndmask_b32_e64 v10, v225, 0, s[44:45]
	v_add_u32_e32 v14, s4, v222
	v_fma_f32 v4, -v154, v4, -v10
	ds_read_b128 v[10:13], v14
	s_mov_b32 s18, 2.0
	s_mov_b32 s20, 0x41200000
	s_mov_b32 s24, 0x41800000
	s_mov_b32 s28, 0x41900000
	s_mov_b32 s19, 0x40400000
	s_mov_b32 s21, 0x41300000
	s_mov_b32 s25, 0x41880000
	s_mov_b32 s29, 0x41980000
	v_fma_f32 v80, 0, v154, v4
	v_add_f32_e32 v81, v154, v4
	v_pk_fma_f32 v[82:83], v[154:155], s[18:19], v[4:5] op_sel_hi:[1,1,0]
	v_pk_fma_f32 v[84:85], v[154:155], s[38:39], v[4:5] op_sel_hi:[1,1,0]
	v_pk_fma_f32 v[86:87], v[154:155], s[20:21], v[4:5] op_sel_hi:[1,1,0]
	v_pk_fma_f32 v[88:89], v[154:155], s[24:25], v[4:5] op_sel_hi:[1,1,0]
	v_pk_fma_f32 v[90:91], v[154:155], s[28:29], v[4:5] op_sel_hi:[1,1,0]
	v_pk_fma_f32 v[92:93], v[154:155], s[26:27], v[4:5] op_sel_hi:[1,1,0]
	v_pk_fma_f32 v[94:95], v[154:155], s[36:37], v[4:5] op_sel_hi:[1,1,0]
	v_add_f32_e32 v4, v153, v4
	v_fma_f32 v96, 0, v154, v4
	s_waitcnt lgkmcnt(0)
	v_mfma_f32_32x32x16_bf16 v[80:95], v[10:13], v[112:115], v[80:95]
	ds_read_b128 v[10:13], v14 offset:32
	v_add_f32_e32 v97, v154, v4
	v_fma_f32 v98, v154, s18, v4
	v_fma_f32 v99, v155, s19, v4
	v_fma_f32 v100, v154, s38, v4
	v_fma_f32 v101, v155, s39, v4
	v_pk_fma_f32 v[102:103], v[154:155], s[20:21], v[4:5] op_sel_hi:[1,1,0]
	v_pk_fma_f32 v[104:105], v[154:155], s[24:25], v[4:5] op_sel_hi:[1,1,0]
	v_pk_fma_f32 v[106:107], v[154:155], s[28:29], v[4:5] op_sel_hi:[1,1,0]
	s_waitcnt lgkmcnt(0)
	v_mfma_f32_32x32x16_bf16 v[80:95], v[10:13], v[116:119], v[80:95]
	ds_read_b128 v[10:13], v14 offset:64
	v_fma_f32 v108, v154, s26, v4
	v_fma_f32 v109, v155, s27, v4
	v_fma_f32 v110, v154, s36, v4
	v_fma_f32 v111, v155, s37, v4
	s_cmp_lg_u32 s22, s7
	s_waitcnt lgkmcnt(0)
	v_mfma_f32_32x32x16_bf16 v[80:95], v[10:13], v[120:123], v[80:95]
	ds_read_b128 v[10:13], v14 offset:96
	ds_read_b128 v[226:229], v14 offset:4608
	s_waitcnt lgkmcnt(1)
	v_mfma_f32_32x32x16_bf16 v[80:95], v[10:13], v[124:127], v[80:95]
	ds_read_b128 v[10:13], v14 offset:4640
	s_waitcnt lgkmcnt(1)
	v_mfma_f32_32x32x16_bf16 v[96:111], v[226:229], v[112:115], v[96:111]
	s_nop 8
	v_max_f32_e32 v4, v81, v81
	s_waitcnt lgkmcnt(0)
	v_mfma_f32_32x32x16_bf16 v[96:111], v[10:13], v[116:119], v[96:111]
	ds_read_b128 v[10:13], v14 offset:4672
	s_waitcnt lgkmcnt(0)
	v_mfma_f32_32x32x16_bf16 v[96:111], v[10:13], v[120:123], v[96:111]
	ds_read_b128 v[10:13], v14 offset:4704
	s_waitcnt lgkmcnt(0)
	v_mfma_f32_32x32x16_bf16 v[96:111], v[10:13], v[124:127], v[96:111]
	s_nop 11
	v_max3_f32 v10, v97, v82, v98
	v_max3_f32 v4, v4, v83, v99
	v_max3_f32 v10, v10, v80, v96
	v_max3_f32 v4, v4, v84, v100
	v_max3_f32 v10, v10, v85, v101
	v_max3_f32 v4, v4, v86, v102
	v_max3_f32 v10, v10, v87, v103
	v_max3_f32 v4, v4, v88, v104
	v_max3_f32 v10, v10, v89, v105
	v_max3_f32 v4, v4, v90, v106
	v_max3_f32 v10, v10, v91, v107
	v_max3_f32 v4, v4, v92, v108
	v_max3_f32 v10, v10, v93, v109
	v_max3_f32 v4, v4, v94, v110
	v_max3_f32 v10, v10, v95, v111
	v_max_f32_e32 v4, v4, v10
	v_mov_b32_e32 v10, v4
	s_waitcnt lgkmcnt(0)
	s_nop 1
	v_permlane32_swap_b32_e32 v10, v4
	v_max_f32_e32 v4, v4, v10
	v_cmp_lt_f32_e32 vcc, s38, v4
	s_cbranch_scc0 .LBB0_748
	s_cbranch_vccz .LBB0_752
	s_branch .LBB0_749

.LBB0_746:
	v_add_u32_e32 v4, 64, v0
	v_cvt_f32_i32_e32 v4, v4
	s_cmp_eq_u32 s48, s7
	s_cselect_b64 s[44:45], -1, 0
	v_cndmask_b32_e64 v7, v225, 0, s[44:45]
	v_fma_f32 v4, -v154, v4, -v7
	v_add_u32_e32 v7, s23, v222
	ds_read_b128 v[8:11], v7
	s_mov_b32 s18, 2.0
	s_mov_b32 s20, 0x41200000
	s_mov_b32 s24, 0x41800000
	s_mov_b32 s28, 0x41900000
	s_mov_b32 s19, 0x40400000
	s_mov_b32 s21, 0x41300000
	s_mov_b32 s25, 0x41880000
	s_mov_b32 s29, 0x41980000
	v_fma_f32 v80, 0, v154, v4
	v_add_f32_e32 v81, v154, v4
	v_pk_fma_f32 v[82:83], v[154:155], s[18:19], v[4:5] op_sel_hi:[1,1,0]
	v_pk_fma_f32 v[84:85], v[154:155], s[38:39], v[4:5] op_sel_hi:[1,1,0]
	v_pk_fma_f32 v[86:87], v[154:155], s[20:21], v[4:5] op_sel_hi:[1,1,0]
	v_pk_fma_f32 v[88:89], v[154:155], s[24:25], v[4:5] op_sel_hi:[1,1,0]
	v_pk_fma_f32 v[90:91], v[154:155], s[28:29], v[4:5] op_sel_hi:[1,1,0]
	v_pk_fma_f32 v[92:93], v[154:155], s[26:27], v[4:5] op_sel_hi:[1,1,0]
	v_pk_fma_f32 v[94:95], v[154:155], s[36:37], v[4:5] op_sel_hi:[1,1,0]
	v_add_f32_e32 v4, v153, v4
	v_fma_f32 v96, 0, v154, v4
	s_waitcnt lgkmcnt(0)
	v_mfma_f32_32x32x16_bf16 v[80:95], v[8:11], v[112:115], v[80:95]
	ds_read_b128 v[8:11], v7 offset:32
	v_add_f32_e32 v97, v154, v4
	v_fma_f32 v98, v154, s18, v4
	v_fma_f32 v99, v155, s19, v4
	v_fma_f32 v100, v154, s38, v4
	v_fma_f32 v101, v155, s39, v4
	v_pk_fma_f32 v[102:103], v[154:155], s[20:21], v[4:5] op_sel_hi:[1,1,0]
	v_pk_fma_f32 v[104:105], v[154:155], s[24:25], v[4:5] op_sel_hi:[1,1,0]
	v_pk_fma_f32 v[106:107], v[154:155], s[28:29], v[4:5] op_sel_hi:[1,1,0]
	s_waitcnt lgkmcnt(0)
	v_mfma_f32_32x32x16_bf16 v[80:95], v[8:11], v[116:119], v[80:95]
	ds_read_b128 v[8:11], v7 offset:64
	v_fma_f32 v108, v154, s26, v4
	v_fma_f32 v109, v155, s27, v4
	v_fma_f32 v110, v154, s36, v4
	v_fma_f32 v111, v155, s37, v4
	s_cmp_lg_u32 s48, s7
	s_waitcnt lgkmcnt(0)
	v_mfma_f32_32x32x16_bf16 v[80:95], v[8:11], v[120:123], v[80:95]
	ds_read_b128 v[8:11], v7 offset:96
	ds_read_b128 v[12:15], v7 offset:4608
	s_waitcnt lgkmcnt(1)
	v_mfma_f32_32x32x16_bf16 v[80:95], v[8:11], v[124:127], v[80:95]
	ds_read_b128 v[8:11], v7 offset:4640
	s_waitcnt lgkmcnt(1)
	v_mfma_f32_32x32x16_bf16 v[96:111], v[12:15], v[112:115], v[96:111]
	s_nop 8
	v_max_f32_e32 v4, v81, v81
	s_waitcnt lgkmcnt(0)
	v_mfma_f32_32x32x16_bf16 v[96:111], v[8:11], v[116:119], v[96:111]
	ds_read_b128 v[8:11], v7 offset:4672
	s_waitcnt lgkmcnt(0)
	v_mfma_f32_32x32x16_bf16 v[96:111], v[8:11], v[120:123], v[96:111]
	ds_read_b128 v[8:11], v7 offset:4704
	s_waitcnt lgkmcnt(0)
	v_mfma_f32_32x32x16_bf16 v[96:111], v[8:11], v[124:127], v[96:111]
	s_nop 11
	v_max3_f32 v7, v97, v82, v98
	v_max3_f32 v4, v4, v83, v99
	v_max3_f32 v7, v7, v80, v96
	v_max3_f32 v4, v4, v84, v100
	v_max3_f32 v7, v7, v85, v101
	v_max3_f32 v4, v4, v86, v102
	v_max3_f32 v7, v7, v87, v103
	v_max3_f32 v4, v4, v88, v104
	v_max3_f32 v7, v7, v89, v105
	v_max3_f32 v4, v4, v90, v106
	v_max3_f32 v7, v7, v91, v107
	v_max3_f32 v4, v4, v92, v108
	v_max3_f32 v7, v7, v93, v109
	v_max3_f32 v4, v4, v94, v110
	v_max3_f32 v7, v7, v95, v111
	v_max_f32_e32 v4, v4, v7
	v_mov_b32_e32 v7, v4
	s_waitcnt lgkmcnt(0)
	s_nop 1
	v_permlane32_swap_b32_e32 v7, v4
	v_max_f32_e32 v4, v4, v7
	v_cmp_lt_f32_e32 vcc, s38, v4
	s_cbranch_scc0 .LBB0_753
	s_cbranch_vccz .LBB0_757
	s_branch .LBB0_754
